# P9 epilogue: 16 residual loads hoisted up front, 8rows x 128B wide loads/stores via DPP half exchange, stores+atomics at end; plus P7 wide-store epilogue
# speedup vs baseline: 1.0106x; 1.0071x over previous
; #define G8_STAGE(bufoff, gbase, NM) do { _Pragma("unroll") for (int _i = 0; _i < 2; ++_i) { \
;     const char* _b = (const char*)(gbase) + (_i ? p2##NM : (size_t)0); asm volatile("" : "+s"(_b));     \
;     __builtin_amdgcn_global_load_lds((const unsigned*)(_b + voff##NM), (LAS unsigned*)(lds + (bufoff) + ldsw + _i * 8192), 16, 0, 0); } } while (0)
; #define G8_WAIT_V(n) asm volatile("s_waitcnt vmcnt(" #n ")" ::: "memory")
; #define G8_BAR __builtin_amdgcn_s_barrier()
;     ...
;   const int wid = __builtin_amdgcn_readfirstlane(tid >> 6), lane = tid & 63, wr = wid >> 2, wc = wid & 3, fr = lane & 15, fq = lane >> 4;
;   const int nt = K / BK;
;   unsigned voffA, voffB;
;   { int R, C; stage_rc(tid * 16, R, C); const int Rb = (R & ~31) + perm32(R & 31); voffA = (unsigned)(R * lda + C) * 2u; voffB = (unsigned)(Rb * ldb + C) * 2u; }
;   const size_t p2A = (size_t)64 * lda * 2, p2B = (size_t)64 * ldb * 2;
;   const size_t kstep = (size_t)(BK * 2);
;   const size_t hstepA = (size_t)HALF * lda * 2, hstepB = (size_t)HALF * ldb * 2;
;   const unsigned ldsw = (unsigned)wid * 1024u;
;   const int aoff = lds_byte(wr * 64 + fr, fq * 8), boff = lds_byte(wc * 32 + fr, fq * 8);
;     ...
;   G8_WAIT_V(2); G8_BAR;
;   G8_STAGE(G8_SB(1, 0), cB + kstep, B); G8_STAGE(G8_SA(1, 0), cA + kstep, A); G8_STAGE(G8_SB(1, 1), cB + hstepB + kstep, B);
;   G8_WAIT_V(6); G8_BAR;
.LBB0_1205:
	v_readlane_b32 s12, v254, 16
	v_readlane_b32 s14, v254, 18
	v_readlane_b32 s15, v254, 19
	s_add_u32 s4, s14, 0x3eb40000
	s_addc_u32 s5, s15, 0
	s_lshl_b32 s7, s7, 13
	s_lshl_b32 s10, s8, 13
	s_and_b32 s7, s7, 0x6000
	s_add_u32 s8, s20, 0x80
	s_addc_u32 s9, s21, 0
	s_waitcnt vmcnt(2)
	s_barrier
	s_add_i32 m0, s29, 0x18000
	v_and_b32_e32 v1, 15, v0
	v_lshl_add_u64 v[2:3], s[8:9], 0, v[130:131]
	s_add_u32 s8, s20, 0x80080
	s_addc_u32 s9, s21, 0
	global_load_lds_dwordx4 v[2:3], off
	s_add_i32 m0, s29, 0x1a000
	v_lshl_add_u64 v[2:3], s[8:9], 0, v[130:131]
	s_add_u32 s8, s18, 0x80
	s_addc_u32 s9, s19, 0
	global_load_lds_dwordx4 v[2:3], off
	s_add_i32 s35, s29, 0x8000
	v_lshl_add_u64 v[2:3], s[8:9], 0, v[128:129]
	s_add_u32 s8, s18, 0x80080
	s_mov_b32 m0, s35
	s_addc_u32 s9, s19, 0
	global_load_lds_dwordx4 v[2:3], off
	s_add_i32 s36, s29, 0xa000
	v_lshl_add_u64 v[2:3], s[8:9], 0, v[128:129]
	s_add_u32 s8, s20, 0x100080
	s_mov_b32 m0, s36
	s_addc_u32 s9, s21, 0
	global_load_lds_dwordx4 v[2:3], off
	s_add_i32 m0, s29, 0x1c000
	v_lshlrev_b32_e32 v1, 6, v1
	v_lshl_add_u64 v[2:3], s[8:9], 0, v[130:131]
	s_add_u32 s8, s20, 0x180080
	s_addc_u32 s9, s21, 0
	global_load_lds_dwordx4 v[2:3], off
	s_add_i32 m0, s29, 0x1e000
	v_lshl_add_u64 v[2:3], s[8:9], 0, v[130:131]
	global_load_lds_dwordx4 v[2:3], off
	v_and_b32_e32 v2, 48, v0
	v_lshlrev_b32_e32 v0, 2, v0
	v_and_b32_e32 v0, 32, v0
	v_or_b32_e32 v3, v1, v2
	v_bitop3_b32 v1, v1, v0, v2 bitop3:0x36
	s_waitcnt vmcnt(6)
	s_cmpk_lt_u32 s6, 0x100
	v_readlane_b32 s13, v254, 17
	v_bitop3_b32 v0, v3, s10, v0 bitop3:0xde
	v_or_b32_e32 v136, s7, v1
	s_cselect_b64 s[6:7], -1, 0
	s_add_i32 s37, 0, 0x10000
	s_add_i32 s38, 0, 0x14000
	v_add_u32_e32 v137, s37, v136
	v_add_u32_e32 v138, 0x1000, v137
	v_add_u32_e32 v139, 0, v0
	s_movk_i32 s39, 0x1080
	s_mov_b64 s[12:13], s[18:19]
	s_mov_b64 s[14:15], s[20:21]
	s_barrier
	s_branch .LBB0_1208

; #define G8_STAGE(bufoff, gbase, NM) do { _Pragma("unroll") for (int _i = 0; _i < 2; ++_i) { \
;     const char* _b = (const char*)(gbase) + (_i ? p2##NM : (size_t)0); asm volatile("" : "+s"(_b));     \
;     __builtin_amdgcn_global_load_lds((const unsigned*)(_b + voff##NM), (LAS unsigned*)(lds + (bufoff) + ldsw + _i * 8192), 16, 0, 0); } } while (0)
; #define G8_WAIT_V(n) asm volatile("s_waitcnt vmcnt(" #n ")" ::: "memory")
; #define G8_WAIT_L(n) asm volatile("s_waitcnt lgkmcnt(" #n ")" ::: "memory")
; #define G8_BAR __builtin_amdgcn_s_barrier()
; #define G8_SCHED __builtin_amdgcn_sched_barrier(0)
;     ...
;     for (int t = 0; t < nt; t += 2) {
;       const bool last = (t == nt - 2);
;       const char* a1 = cA + (size_t)(t + 1) * kstep + hstepA;
;       const char* a2 = last ? nA : cA + (size_t)(t + 2) * kstep; const char* b2 = last ? nB : cB + (size_t)(t + 2) * kstep;
;       const char* a3 = a2 + kstep; const char* b3 = b2 + kstep;
;       asm volatile("" : "+s"(a1), "+s"(a2), "+s"(b2), "+s"(a3), "+s"(b3));
;       G8_LDB(B0, 0, 0); G8_LDB(B1, 0, 1); G8_SCHED; G8_LDA(At, 0, 0); G8_STAGE(G8_SA(1, 1), a1, A);
;       const bool d0a = (BD == 0) || (BD == 1 && t < (nt >> 1)) || (BD == 2 && !(cur.pn & 1));
;       const bool d1a = (BD == 0) || (BD == 1 && t >= (nt >> 1)) || (BD == 2 && !(cur.pn & 1));
;       const bool d0b = (BD == 0) || (BD == 1 && t < (nt >> 1)) || (BD == 2 && (cur.pn & 1));
;       const bool d1b = (BD == 0) || (BD == 1 && t >= (nt >> 1)) || (BD == 2 && (cur.pn & 1));
;       G8_WAIT_V(8); G8_WAIT_L(0); G8_BAR; if (d0a) G8_MMA(0, 0, At, B0); if (d1a) G8_MMA(0, 1, At, B1); G8_BAR; G8_SCHED;
;       G8_LDA(At, 0, 1); G8_STAGE(G8_SB(0, 0), b2, B); G8_STAGE(G8_SB(0, 1), b2 + hstepB, B); G8_STAGE(G8_SA(0, 0), a2, A);
;       G8_WAIT_V(8); G8_WAIT_L(0); G8_BAR; if (d0a) G8_MMA(1, 0, At, B0); if (d1a) G8_MMA(1, 1, At, B1); G8_BAR; G8_SCHED;
.LBB0_1215:
	s_add_u32 s44, s18, 0x100080
	s_addc_u32 s45, s19, 0
	s_add_u32 s18, s18, 0x100
	s_addc_u32 s19, s19, 0
	s_cmp_eq_u32 s42, 60
	s_cselect_b32 s24, s12, s18
	s_cselect_b32 s25, s13, s19
	s_cselect_b32 s27, s15, s17
	s_cselect_b32 s26, s14, s11
	s_add_u32 s20, s24, 0x80
	s_addc_u32 s21, s25, 0
	s_add_u32 s22, s26, 0x80
	s_addc_u32 s23, s27, 0
	ds_read_b128 v[132:135], v137
	ds_read_b128 v[140:143], v137 offset:1024
	ds_read_b128 v[144:147], v137 offset:2048
	ds_read_b128 v[148:151], v137 offset:3072
	ds_read_b128 v[152:155], v138
	ds_read_b128 v[156:159], v138 offset:1024
	ds_read_b128 v[160:163], v138 offset:2048
	ds_read_b128 v[164:167], v138 offset:3072
	s_add_i32 m0, s29, 0xc000
	s_mov_b64 s[46:47], s[44:45]
	s_add_u32 s44, s44, 0x80000
	ds_read_b128 v[168:171], v139
	ds_read_b128 v[172:175], v139 offset:1024
	ds_read_b128 v[176:179], v139 offset:2048
	ds_read_b128 v[180:183], v139 offset:3072
	ds_read_b128 v[184:187], v139 offset:4096
	ds_read_b128 v[188:191], v139 offset:5120
	ds_read_b128 v[192:195], v139 offset:6144
	ds_read_b128 v[196:199], v139 offset:7168
	s_addc_u32 s45, s45, 0
	v_lshl_add_u64 v[202:203], s[46:47], 0, v[128:129]
	global_load_lds_dwordx4 v[202:203], off
	s_add_i32 m0, s29, 0xe000
	v_lshl_add_u64 v[202:203], s[44:45], 0, v[128:129]
	global_load_lds_dwordx4 v[202:203], off
	s_waitcnt vmcnt(8)
	s_waitcnt lgkmcnt(0)
	s_barrier
	s_setprio 1
	s_waitcnt lgkmcnt(0)
	v_mfma_f32_16x16x32_bf16 v[124:127], v[132:135], v[168:171], v[124:127]
	v_mfma_f32_16x16x32_bf16 v[120:123], v[144:147], v[168:171], v[120:123]
	v_mfma_f32_16x16x32_bf16 v[108:111], v[132:135], v[176:179], v[108:111]
	v_mfma_f32_16x16x32_bf16 v[104:107], v[144:147], v[176:179], v[104:107]
	v_mfma_f32_16x16x32_bf16 v[92:95], v[132:135], v[184:187], v[92:95]
	v_mfma_f32_16x16x32_bf16 v[88:91], v[144:147], v[184:187], v[88:91]
	v_mfma_f32_16x16x32_bf16 v[76:79], v[132:135], v[192:195], v[76:79]
	v_mfma_f32_16x16x32_bf16 v[72:75], v[144:147], v[192:195], v[72:75]
	v_mfma_f32_16x16x32_bf16 v[124:127], v[140:143], v[172:175], v[124:127]
	v_mfma_f32_16x16x32_bf16 v[120:123], v[148:151], v[172:175], v[120:123]
	v_mfma_f32_16x16x32_bf16 v[108:111], v[140:143], v[180:183], v[108:111]
	v_mfma_f32_16x16x32_bf16 v[104:107], v[148:151], v[180:183], v[104:107]
	v_mfma_f32_16x16x32_bf16 v[92:95], v[140:143], v[188:191], v[92:95]
	v_mfma_f32_16x16x32_bf16 v[88:91], v[148:151], v[188:191], v[88:91]
	v_mfma_f32_16x16x32_bf16 v[76:79], v[140:143], v[196:199], v[76:79]
	v_mfma_f32_16x16x32_bf16 v[72:75], v[148:151], v[196:199], v[72:75]
	s_setprio 0
	s_setprio 1
	v_mfma_f32_16x16x32_bf16 v[116:119], v[152:155], v[168:171], v[116:119]
	v_mfma_f32_16x16x32_bf16 v[112:115], v[160:163], v[168:171], v[112:115]
	v_mfma_f32_16x16x32_bf16 v[100:103], v[152:155], v[176:179], v[100:103]
	v_mfma_f32_16x16x32_bf16 v[96:99], v[160:163], v[176:179], v[96:99]
	v_mfma_f32_16x16x32_bf16 v[84:87], v[152:155], v[184:187], v[84:87]
	v_mfma_f32_16x16x32_bf16 v[80:83], v[160:163], v[184:187], v[80:83]
	v_mfma_f32_16x16x32_bf16 v[68:71], v[152:155], v[192:195], v[68:71]
	v_mfma_f32_16x16x32_bf16 v[64:67], v[160:163], v[192:195], v[64:67]
	v_mfma_f32_16x16x32_bf16 v[116:119], v[156:159], v[172:175], v[116:119]
	v_mfma_f32_16x16x32_bf16 v[112:115], v[164:167], v[172:175], v[112:115]
	v_mfma_f32_16x16x32_bf16 v[100:103], v[156:159], v[180:183], v[100:103]
	v_mfma_f32_16x16x32_bf16 v[96:99], v[164:167], v[180:183], v[96:99]
	v_mfma_f32_16x16x32_bf16 v[84:87], v[156:159], v[188:191], v[84:87]
	v_mfma_f32_16x16x32_bf16 v[80:83], v[164:167], v[188:191], v[80:83]
	v_mfma_f32_16x16x32_bf16 v[68:71], v[156:159], v[196:199], v[68:71]
	v_mfma_f32_16x16x32_bf16 v[64:67], v[164:167], v[196:199], v[64:67]
	s_setprio 0
	s_barrier
	s_mov_b64 s[44:45], s[26:27]
	ds_read_b128 v[168:171], v139 offset:16384
	ds_read_b128 v[172:175], v139 offset:17408
	ds_read_b128 v[176:179], v139 offset:18432
	ds_read_b128 v[180:183], v139 offset:19456
	ds_read_b128 v[184:187], v139 offset:20480
	ds_read_b128 v[188:191], v139 offset:21504
	ds_read_b128 v[192:195], v139 offset:22528
	ds_read_b128 v[196:199], v139 offset:23552
	s_add_i32 s43, s37, s28
	v_lshl_add_u64 v[202:203], s[44:45], 0, v[130:131]
	s_add_u32 s44, s26, 0x80000
	s_mov_b32 m0, s43
	s_addc_u32 s45, s27, 0
	global_load_lds_dwordx4 v[202:203], off
	s_add_i32 m0, s43, 0x2000
	v_lshl_add_u64 v[202:203], s[44:45], 0, v[130:131]
	s_add_u32 s44, s26, 0x100000
	s_addc_u32 s45, s27, 0
	s_add_i32 s43, s38, s28
	s_add_u32 s26, s26, 0x180000
	global_load_lds_dwordx4 v[202:203], off
	s_mov_b32 m0, s43
	v_lshl_add_u64 v[202:203], s[44:45], 0, v[130:131]
	s_addc_u32 s27, s27, 0
	global_load_lds_dwordx4 v[202:203], off
	s_add_i32 m0, s43, 0x2000
	v_lshl_add_u64 v[202:203], s[26:27], 0, v[130:131]
	s_mov_b64 s[26:27], s[24:25]
	global_load_lds_dwordx4 v[202:203], off
	s_mov_b32 m0, s29
	v_lshl_add_u64 v[202:203], s[26:27], 0, v[128:129]
	s_add_u32 s26, s24, 0x80000
	s_addc_u32 s27, s25, 0
	global_load_lds_dwordx4 v[202:203], off
	s_mov_b32 m0, s30
	v_lshl_add_u64 v[202:203], s[26:27], 0, v[128:129]
	global_load_lds_dwordx4 v[202:203], off
	s_waitcnt vmcnt(8)
	s_waitcnt lgkmcnt(0)
	s_barrier
; #define G8_STAGE(bufoff, gbase, NM) do { _Pragma("unroll") for (int _i = 0; _i < 2; ++_i) { \
;     const char* _b = (const char*)(gbase) + (_i ? p2##NM : (size_t)0); asm volatile("" : "+s"(_b));     \
;     __builtin_amdgcn_global_load_lds((const unsigned*)(_b + voff##NM), (LAS unsigned*)(lds + (bufoff) + ldsw + _i * 8192), 16, 0, 0); } } while (0)
; #define G8_WAIT_V(n) asm volatile("s_waitcnt vmcnt(" #n ")" ::: "memory")
; #define G8_WAIT_L(n) asm volatile("s_waitcnt lgkmcnt(" #n ")" ::: "memory")
; #define G8_BAR __builtin_amdgcn_s_barrier()
; #define G8_SCHED __builtin_amdgcn_sched_barrier(0)
;     ...
;       G8_WAIT_V(8); G8_WAIT_L(0); G8_BAR; if (d0a) G8_MMA(1, 0, At, B0); if (d1a) G8_MMA(1, 1, At, B1); G8_BAR; G8_SCHED;
;       G8_LDB(B0, 1, 0); G8_LDB(B1, 1, 1); G8_SCHED; G8_LDA(At, 1, 0); G8_STAGE(G8_SA(0, 1), a2 + hstepA, A);
;       G8_WAIT_V(8); G8_WAIT_L(0); G8_BAR; if (d0b) G8_MMA(0, 0, At, B0); if (d1b) G8_MMA(0, 1, At, B1); G8_BAR; G8_SCHED;
;       G8_LDA(At, 1, 1); G8_STAGE(G8_SB(1, 0), b3, B); G8_STAGE(G8_SB(1, 1), b3 + hstepB, B); G8_STAGE(G8_SA(1, 0), a3, A);
	s_setprio 1
	s_waitcnt lgkmcnt(0)
	v_mfma_f32_16x16x32_bf16 v[60:63], v[132:135], v[168:171], v[60:63]
	v_mfma_f32_16x16x32_bf16 v[56:59], v[144:147], v[168:171], v[56:59]
	v_mfma_f32_16x16x32_bf16 v[44:47], v[132:135], v[176:179], v[44:47]
	v_mfma_f32_16x16x32_bf16 v[40:43], v[144:147], v[176:179], v[40:43]
	v_mfma_f32_16x16x32_bf16 v[28:31], v[132:135], v[184:187], v[28:31]
	v_mfma_f32_16x16x32_bf16 v[24:27], v[144:147], v[184:187], v[24:27]
	v_mfma_f32_16x16x32_bf16 v[12:15], v[132:135], v[192:195], v[12:15]
	v_mfma_f32_16x16x32_bf16 v[8:11], v[144:147], v[192:195], v[8:11]
	v_mfma_f32_16x16x32_bf16 v[60:63], v[140:143], v[172:175], v[60:63]
	v_mfma_f32_16x16x32_bf16 v[56:59], v[148:151], v[172:175], v[56:59]
	v_mfma_f32_16x16x32_bf16 v[44:47], v[140:143], v[180:183], v[44:47]
	v_mfma_f32_16x16x32_bf16 v[40:43], v[148:151], v[180:183], v[40:43]
	v_mfma_f32_16x16x32_bf16 v[28:31], v[140:143], v[188:191], v[28:31]
	v_mfma_f32_16x16x32_bf16 v[24:27], v[148:151], v[188:191], v[24:27]
	v_mfma_f32_16x16x32_bf16 v[12:15], v[140:143], v[196:199], v[12:15]
	v_mfma_f32_16x16x32_bf16 v[8:11], v[148:151], v[196:199], v[8:11]
	s_setprio 0
	s_setprio 1
	v_mfma_f32_16x16x32_bf16 v[52:55], v[152:155], v[168:171], v[52:55]
	v_mfma_f32_16x16x32_bf16 v[48:51], v[160:163], v[168:171], v[48:51]
	v_mfma_f32_16x16x32_bf16 v[36:39], v[152:155], v[176:179], v[36:39]
	v_mfma_f32_16x16x32_bf16 v[32:35], v[160:163], v[176:179], v[32:35]
	v_mfma_f32_16x16x32_bf16 v[20:23], v[152:155], v[184:187], v[20:23]
	v_mfma_f32_16x16x32_bf16 v[16:19], v[160:163], v[184:187], v[16:19]
	v_mfma_f32_16x16x32_bf16 v[4:7], v[152:155], v[192:195], v[4:7]
	v_mfma_f32_16x16x32_bf16 v[0:3], v[160:163], v[192:195], v[0:3]
	v_mfma_f32_16x16x32_bf16 v[52:55], v[156:159], v[172:175], v[52:55]
	v_mfma_f32_16x16x32_bf16 v[48:51], v[164:167], v[172:175], v[48:51]
	v_mfma_f32_16x16x32_bf16 v[36:39], v[156:159], v[180:183], v[36:39]
	v_mfma_f32_16x16x32_bf16 v[32:35], v[164:167], v[180:183], v[32:35]
	v_mfma_f32_16x16x32_bf16 v[20:23], v[156:159], v[188:191], v[20:23]
	v_mfma_f32_16x16x32_bf16 v[16:19], v[164:167], v[188:191], v[16:19]
	v_mfma_f32_16x16x32_bf16 v[4:7], v[156:159], v[196:199], v[4:7]
	v_mfma_f32_16x16x32_bf16 v[0:3], v[164:167], v[196:199], v[0:3]
	s_setprio 0
	s_barrier
	s_add_i32 s43, 0, 0x18000
	s_add_i32 s44, 0, 0x1c000
	v_add_u32_e32 v148, s43, v136
	v_add_u32_e32 v164, 0x1000, v148
	ds_read_b128 v[132:135], v148
	ds_read_b128 v[140:143], v148 offset:1024
	ds_read_b128 v[144:147], v148 offset:2048
	ds_read_b128 v[148:151], v148 offset:3072
	ds_read_b128 v[152:155], v164
	ds_read_b128 v[156:159], v164 offset:1024
	ds_read_b128 v[160:163], v164 offset:2048
	ds_read_b128 v[164:167], v164 offset:3072
	s_add_u32 s26, s24, 0x100000
	s_addc_u32 s27, s25, 0
	s_add_u32 s24, s24, 0x180000
	s_mov_b32 m0, s31
	ds_read_b128 v[168:171], v139 offset:32768
	ds_read_b128 v[172:175], v139 offset:33792
	ds_read_b128 v[176:179], v139 offset:34816
	ds_read_b128 v[180:183], v139 offset:35840
	ds_read_b128 v[184:187], v139 offset:36864
	ds_read_b128 v[188:191], v139 offset:37888
	ds_read_b128 v[192:195], v139 offset:38912
	ds_read_b128 v[196:199], v139 offset:39936
	s_addc_u32 s25, s25, 0
	v_lshl_add_u64 v[202:203], s[26:27], 0, v[128:129]
	global_load_lds_dwordx4 v[202:203], off
	s_mov_b32 m0, s33
	v_lshl_add_u64 v[202:203], s[24:25], 0, v[128:129]
	global_load_lds_dwordx4 v[202:203], off
	s_waitcnt vmcnt(8)
	s_waitcnt lgkmcnt(0)
	s_barrier
	s_setprio 1
	s_waitcnt lgkmcnt(0)
	v_mfma_f32_16x16x32_bf16 v[124:127], v[132:135], v[168:171], v[124:127]
	v_mfma_f32_16x16x32_bf16 v[120:123], v[144:147], v[168:171], v[120:123]
	v_mfma_f32_16x16x32_bf16 v[108:111], v[132:135], v[176:179], v[108:111]
	v_mfma_f32_16x16x32_bf16 v[104:107], v[144:147], v[176:179], v[104:107]
	v_mfma_f32_16x16x32_bf16 v[92:95], v[132:135], v[184:187], v[92:95]
	v_mfma_f32_16x16x32_bf16 v[88:91], v[144:147], v[184:187], v[88:91]
	v_mfma_f32_16x16x32_bf16 v[76:79], v[132:135], v[192:195], v[76:79]
	v_mfma_f32_16x16x32_bf16 v[72:75], v[144:147], v[192:195], v[72:75]
	v_mfma_f32_16x16x32_bf16 v[124:127], v[140:143], v[172:175], v[124:127]
	v_mfma_f32_16x16x32_bf16 v[120:123], v[148:151], v[172:175], v[120:123]
	v_mfma_f32_16x16x32_bf16 v[108:111], v[140:143], v[180:183], v[108:111]
	v_mfma_f32_16x16x32_bf16 v[104:107], v[148:151], v[180:183], v[104:107]
	v_mfma_f32_16x16x32_bf16 v[92:95], v[140:143], v[188:191], v[92:95]
	v_mfma_f32_16x16x32_bf16 v[88:91], v[148:151], v[188:191], v[88:91]
	v_mfma_f32_16x16x32_bf16 v[76:79], v[140:143], v[196:199], v[76:79]
	v_mfma_f32_16x16x32_bf16 v[72:75], v[148:151], v[196:199], v[72:75]
	s_setprio 0
	s_setprio 1
	v_mfma_f32_16x16x32_bf16 v[116:119], v[152:155], v[168:171], v[116:119]
	v_mfma_f32_16x16x32_bf16 v[112:115], v[160:163], v[168:171], v[112:115]
	v_mfma_f32_16x16x32_bf16 v[100:103], v[152:155], v[176:179], v[100:103]
	v_mfma_f32_16x16x32_bf16 v[96:99], v[160:163], v[176:179], v[96:99]
	v_mfma_f32_16x16x32_bf16 v[84:87], v[152:155], v[184:187], v[84:87]
	v_mfma_f32_16x16x32_bf16 v[80:83], v[160:163], v[184:187], v[80:83]
	v_mfma_f32_16x16x32_bf16 v[68:71], v[152:155], v[192:195], v[68:71]
	v_mfma_f32_16x16x32_bf16 v[64:67], v[160:163], v[192:195], v[64:67]
	v_mfma_f32_16x16x32_bf16 v[116:119], v[156:159], v[172:175], v[116:119]
	v_mfma_f32_16x16x32_bf16 v[112:115], v[164:167], v[172:175], v[112:115]
	v_mfma_f32_16x16x32_bf16 v[100:103], v[156:159], v[180:183], v[100:103]
	v_mfma_f32_16x16x32_bf16 v[96:99], v[164:167], v[180:183], v[96:99]
	v_mfma_f32_16x16x32_bf16 v[84:87], v[156:159], v[188:191], v[84:87]
	v_mfma_f32_16x16x32_bf16 v[80:83], v[164:167], v[188:191], v[80:83]
	v_mfma_f32_16x16x32_bf16 v[68:71], v[156:159], v[196:199], v[68:71]
	v_mfma_f32_16x16x32_bf16 v[64:67], v[164:167], v[196:199], v[64:67]
	s_setprio 0
	s_barrier
; #define G8_STAGE(bufoff, gbase, NM) do { _Pragma("unroll") for (int _i = 0; _i < 2; ++_i) { \
;     const char* _b = (const char*)(gbase) + (_i ? p2##NM : (size_t)0); asm volatile("" : "+s"(_b));     \
;     __builtin_amdgcn_global_load_lds((const unsigned*)(_b + voff##NM), (LAS unsigned*)(lds + (bufoff) + ldsw + _i * 8192), 16, 0, 0); } } while (0)
; #define G8_WAIT_V(n) asm volatile("s_waitcnt vmcnt(" #n ")" ::: "memory")
; #define G8_WAIT_L(n) asm volatile("s_waitcnt lgkmcnt(" #n ")" ::: "memory")
; #define G8_BAR __builtin_amdgcn_s_barrier()
; #define G8_SCHED __builtin_amdgcn_sched_barrier(0)
;     ...
;       G8_WAIT_V(8); G8_WAIT_L(0); G8_BAR; if (d0b) G8_MMA(0, 0, At, B0); if (d1b) G8_MMA(0, 1, At, B1); G8_BAR; G8_SCHED;
;       G8_LDA(At, 1, 1); G8_STAGE(G8_SB(1, 0), b3, B); G8_STAGE(G8_SB(1, 1), b3 + hstepB, B); G8_STAGE(G8_SA(1, 0), a3, A);
;       G8_WAIT_V(8); G8_WAIT_L(0); G8_BAR; if (d0b) G8_MMA(1, 0, At, B0); if (d1b) G8_MMA(1, 1, At, B1); G8_BAR; G8_SCHED;
;     }
;     if (wr == 0) G8_BAR;
;   __device__ __forceinline__ void operator()(const Acc& acc, const GUnit& u, int wr, int wc, int fr, int fq) const {
;     const int row0 = u.pm * 256 + wr * 64 + fr; const int col0 = u.pn * 256 + wc * 32 + 8 * fq;
; #pragma unroll
;     for (int ai = 0; ai < 2; ++ai)
; #pragma unroll
;       for (int m = 0; m < 4; ++m) {
;         const int row = row0 + ai * 128 + m * 16; const size_t off = (size_t)row * 2048 + col0; float s = 0.f;
; #pragma unroll
;         for (int bj = 0; bj < 2; ++bj) {
;           f32x4 r0, r1;
;           if (R) { r0 = *(const f32x4*)(R + off + bj * 128); r1 = *(const f32x4*)(R + off + bj * 128 + 4); }
;           else { const u32x4 rw = *(const u32x4*)(RB + (size_t)row * ldrb + col0 + bj * 128);
	s_mov_b64 s[24:25], s[22:23]
	ds_read_b128 v[168:171], v139 offset:49152
	ds_read_b128 v[172:175], v139 offset:50176
	ds_read_b128 v[176:179], v139 offset:51200
	ds_read_b128 v[180:183], v139 offset:52224
	ds_read_b128 v[184:187], v139 offset:53248
	ds_read_b128 v[188:191], v139 offset:54272
	ds_read_b128 v[192:195], v139 offset:55296
	ds_read_b128 v[196:199], v139 offset:56320
	s_add_i32 s26, s43, s28
	v_lshl_add_u64 v[202:203], s[24:25], 0, v[130:131]
	s_add_u32 s24, s22, 0x80000
	s_mov_b32 m0, s26
	s_addc_u32 s25, s23, 0
	global_load_lds_dwordx4 v[202:203], off
	s_add_i32 m0, s26, 0x2000
	v_lshl_add_u64 v[202:203], s[24:25], 0, v[130:131]
	s_add_u32 s24, s22, 0x100000
	s_addc_u32 s25, s23, 0
	global_load_lds_dwordx4 v[202:203], off
	s_nop 0
	v_lshl_add_u64 v[202:203], s[24:25], 0, v[130:131]
	s_add_i32 s24, s44, s28
	s_add_u32 s22, s22, 0x180000
	s_mov_b32 m0, s24
	s_addc_u32 s23, s23, 0
	global_load_lds_dwordx4 v[202:203], off
	s_add_i32 m0, s24, 0x2000
	v_lshl_add_u64 v[202:203], s[22:23], 0, v[130:131]
	s_mov_b64 s[22:23], s[20:21]
	s_add_u32 s20, s20, 0x80000
	global_load_lds_dwordx4 v[202:203], off
	s_mov_b32 m0, s35
	v_lshl_add_u64 v[202:203], s[22:23], 0, v[128:129]
	s_addc_u32 s21, s21, 0
	global_load_lds_dwordx4 v[202:203], off
	s_mov_b32 m0, s36
	v_lshl_add_u64 v[202:203], s[20:21], 0, v[128:129]
	global_load_lds_dwordx4 v[202:203], off
	s_waitcnt vmcnt(8)
	s_waitcnt lgkmcnt(0)
	s_barrier
	s_setprio 1
	s_waitcnt lgkmcnt(0)
	v_mfma_f32_16x16x32_bf16 v[60:63], v[132:135], v[168:171], v[60:63]
	v_mfma_f32_16x16x32_bf16 v[56:59], v[144:147], v[168:171], v[56:59]
	v_mfma_f32_16x16x32_bf16 v[44:47], v[132:135], v[176:179], v[44:47]
	v_mfma_f32_16x16x32_bf16 v[40:43], v[144:147], v[176:179], v[40:43]
	v_mfma_f32_16x16x32_bf16 v[28:31], v[132:135], v[184:187], v[28:31]
	v_mfma_f32_16x16x32_bf16 v[24:27], v[144:147], v[184:187], v[24:27]
	v_mfma_f32_16x16x32_bf16 v[12:15], v[132:135], v[192:195], v[12:15]
	v_mfma_f32_16x16x32_bf16 v[8:11], v[144:147], v[192:195], v[8:11]
	v_mfma_f32_16x16x32_bf16 v[60:63], v[140:143], v[172:175], v[60:63]
	v_mfma_f32_16x16x32_bf16 v[56:59], v[148:151], v[172:175], v[56:59]
	v_mfma_f32_16x16x32_bf16 v[44:47], v[140:143], v[180:183], v[44:47]
	v_mfma_f32_16x16x32_bf16 v[40:43], v[148:151], v[180:183], v[40:43]
	v_mfma_f32_16x16x32_bf16 v[28:31], v[140:143], v[188:191], v[28:31]
	v_mfma_f32_16x16x32_bf16 v[24:27], v[148:151], v[188:191], v[24:27]
	v_mfma_f32_16x16x32_bf16 v[12:15], v[140:143], v[196:199], v[12:15]
	v_mfma_f32_16x16x32_bf16 v[8:11], v[148:151], v[196:199], v[8:11]
	s_setprio 0
	s_setprio 1
	v_mfma_f32_16x16x32_bf16 v[52:55], v[152:155], v[168:171], v[52:55]
	v_mfma_f32_16x16x32_bf16 v[48:51], v[160:163], v[168:171], v[48:51]
	v_mfma_f32_16x16x32_bf16 v[36:39], v[152:155], v[176:179], v[36:39]
	v_mfma_f32_16x16x32_bf16 v[32:35], v[160:163], v[176:179], v[32:35]
	v_mfma_f32_16x16x32_bf16 v[20:23], v[152:155], v[184:187], v[20:23]
	v_mfma_f32_16x16x32_bf16 v[16:19], v[160:163], v[184:187], v[16:19]
	v_mfma_f32_16x16x32_bf16 v[4:7], v[152:155], v[192:195], v[4:7]
	v_mfma_f32_16x16x32_bf16 v[0:3], v[160:163], v[192:195], v[0:3]
	v_mfma_f32_16x16x32_bf16 v[52:55], v[156:159], v[172:175], v[52:55]
	v_mfma_f32_16x16x32_bf16 v[48:51], v[164:167], v[172:175], v[48:51]
	v_mfma_f32_16x16x32_bf16 v[36:39], v[156:159], v[180:183], v[36:39]
	v_mfma_f32_16x16x32_bf16 v[32:35], v[164:167], v[180:183], v[32:35]
	v_mfma_f32_16x16x32_bf16 v[20:23], v[156:159], v[188:191], v[20:23]
	v_mfma_f32_16x16x32_bf16 v[16:19], v[164:167], v[188:191], v[16:19]
	v_mfma_f32_16x16x32_bf16 v[4:7], v[156:159], v[196:199], v[4:7]
	v_mfma_f32_16x16x32_bf16 v[0:3], v[164:167], v[196:199], v[0:3]
	s_setprio 0
	s_barrier
	s_add_i32 s42, s42, 2
	s_add_u32 s11, s11, 0x100
	s_addc_u32 s17, s17, 0
	s_cmp_gt_u32 s42, 61
	s_cbranch_scc0 .LBB0_1215
	s_and_b64 vcc, exec, s[6:7]
	s_cbranch_vccz .LBB0_1218
	s_barrier
.LBB0_1218:
	v_mov_b32_e32 v132, v200
	s_lshl_b32 s16, s16, 8
	v_readfirstlane_b32 s11, v132
	s_ashr_i32 s17, s11, 2
	s_andn2_b32 s17, s17, 63
	s_add_i32 s17, s17, s16
	s_lshl_b32 s16, s41, 8
	s_and_b32 s11, s11, 0xc0
	s_or_b32 s11, s11, s16
	v_bfe_u32 v152, v132, 4, 2
	v_and_or_b32 v134, v132, 15, s17
	v_ashrrev_i32_e32 v135, 31, v134
	v_and_or_b32 v142, v132, 7, s17
	v_and_b32_e32 v143, 8, v132
	v_lshlrev_b32_e32 v143, 2, v143
	v_lshl_or_b32 v143, v152, 3, v143
	v_or_b32_e32 v132, s11, v143
	v_mov_b32_e32 v133, 0
	v_mov_b32_e32 v143, 0
	v_lshlrev_b64 v[132:133], 1, v[132:133]
	v_mov_b64_e32 v[188:189], s[92:93]
	v_readlane_b32 s18, v254, 18
	v_readlane_b32 s19, v254, 19
	v_mad_i64_i32 v[188:189], s[16:17], v142, s39, v[188:189]
	v_lshlrev_b64 v[190:191], 12, v[142:143]
	v_lshl_add_u64 v[188:189], v[188:189], 0, v[132:133]
	v_lshl_add_u64 v[190:191], s[18:19], 0, v[190:191]
	v_lshl_add_u64 v[190:191], v[190:191], 0, v[132:133]
	v_lshl_add_u64 v[140:141], v[134:135], 2, s[4:5]
	v_cmp_eq_u32_e32 vcc, 0, v152
	global_load_dwordx4 v[204:207], v[188:189], off
	s_mov_b64 s[62:63], 0x8400
	v_lshl_add_u64 v[144:145], v[188:189], 0, s[62:63]
	global_load_dwordx4 v[208:211], v[144:145], off
	s_mov_b64 s[60:61], 0x10800
	v_lshl_add_u64 v[142:143], v[188:189], 0, s[60:61]
	global_load_dwordx4 v[212:215], v[142:143], off
	s_mov_b64 s[62:63], 0x18c00
	v_lshl_add_u64 v[144:145], v[188:189], 0, s[62:63]
	global_load_dwordx4 v[216:219], v[144:145], off
	s_mov_b64 s[60:61], 0x21000
	v_lshl_add_u64 v[142:143], v[188:189], 0, s[60:61]
	global_load_dwordx4 v[220:223], v[142:143], off
	s_mov_b64 s[62:63], 0x29400
	v_lshl_add_u64 v[144:145], v[188:189], 0, s[62:63]
	global_load_dwordx4 v[224:227], v[144:145], off
	s_mov_b64 s[60:61], 0x31800
	v_lshl_add_u64 v[142:143], v[188:189], 0, s[60:61]
	global_load_dwordx4 v[228:231], v[142:143], off
	s_mov_b64 s[62:63], 0x39c00
	v_lshl_add_u64 v[144:145], v[188:189], 0, s[62:63]
	global_load_dwordx4 v[232:235], v[144:145], off
	s_mov_b64 s[60:61], 0x84000
	v_lshl_add_u64 v[142:143], v[188:189], 0, s[60:61]
	global_load_dwordx4 v[236:239], v[142:143], off
	s_mov_b64 s[62:63], 0x8c400
	v_lshl_add_u64 v[144:145], v[188:189], 0, s[62:63]
	global_load_dwordx4 v[240:243], v[144:145], off
	s_mov_b64 s[60:61], 0x94800
	v_lshl_add_u64 v[142:143], v[188:189], 0, s[60:61]
	global_load_dwordx4 v[244:247], v[142:143], off
	s_mov_b64 s[62:63], 0x9cc00
	v_lshl_add_u64 v[144:145], v[188:189], 0, s[62:63]
	global_load_dwordx4 v[248:251], v[144:145], off
	s_mov_b64 s[60:61], 0xa5000
	v_lshl_add_u64 v[142:143], v[188:189], 0, s[60:61]
	global_load_dwordx4 v[154:157], v[142:143], off
	s_mov_b64 s[62:63], 0xad400
	v_lshl_add_u64 v[144:145], v[188:189], 0, s[62:63]
	global_load_dwordx4 v[158:161], v[144:145], off
	s_mov_b64 s[60:61], 0xb5800
	v_lshl_add_u64 v[142:143], v[188:189], 0, s[60:61]
	global_load_dwordx4 v[162:165], v[142:143], off
	s_mov_b64 s[62:63], 0xbdc00
	v_lshl_add_u64 v[144:145], v[188:189], 0, s[62:63]
	global_load_dwordx4 v[166:169], v[144:145], off
	s_waitcnt vmcnt(14)
; __device__ __forceinline__ float bflo(unsigned w) { return __uint_as_float(w << 16); }
; __device__ __forceinline__ float bfhi(unsigned w) { return __uint_as_float(w & 0xffff0000u); }
; __device__ __forceinline__ u32x4 pack8(f32x4 a, f32x4 b) { u32x4 w; w[0] = cvt_pk_bf16(a[0], a[1]); w[1] = cvt_pk_bf16(a[2], a[3]); w[2] = cvt_pk_bf16(b[0], b[1]); w[3] = cvt_pk_bf16(b[2], b[3]); return w; }
; __device__ __forceinline__ float psum16(float x) { const u32x2s r = __builtin_amdgcn_permlane16_swap(__float_as_uint(x), __float_as_uint(x), false, false); return __uint_as_float(r[0]) + __uint_as_float(r[1]); }
; __device__ __forceinline__ float psum32(float x) { const u32x2s r = __builtin_amdgcn_permlane32_swap(__float_as_uint(x), __float_as_uint(x), false, false); return __uint_as_float(r[0]) + __uint_as_float(r[1]); }
;   __device__ __forceinline__ void operator()(const Acc& acc, const GUnit& u, int wr, int wc, int fr, int fq) const {
;     ...
;         const int row = row0 + ai * 128 + m * 16; const size_t off = (size_t)row * 2048 + col0; float s = 0.f;
; #pragma unroll
;         for (int bj = 0; bj < 2; ++bj) {
;           f32x4 r0, r1;
;           if (R) { r0 = *(const f32x4*)(R + off + bj * 128); r1 = *(const f32x4*)(R + off + bj * 128 + 4); }
;           else { const u32x4 rw = *(const u32x4*)(RB + (size_t)row * ldrb + col0 + bj * 128);
;             r0 = (f32x4){bflo(rw[0]), bfhi(rw[0]), bflo(rw[1]), bfhi(rw[1])}; r1 = (f32x4){bflo(rw[2]), bfhi(rw[2]), bflo(rw[3]), bfhi(rw[3])}; }
;           const f32x4 h0 = r0 + acc[ai][bj][m][0] * osc, h1 = r1 + acc[ai][bj][m][1] * osc;
;           if (H) { *(f32x4*)(H + off + bj * 128) = h0; *(f32x4*)(H + off + bj * 128 + 4) = h1; }
;           if (HB) *(u32x4*)(HB + (size_t)row * ldhb + col0 + bj * 128) = pack8(h0, h1);
;           s += h0[0] * h0[0] + h0[1] * h0[1] + h0[2] * h0[2] + h0[3] * h0[3] + h1[0] * h1[0] + h1[1] * h1[1] + h1[2] * h1[2] + h1[3] * h1[3];
;         }
;         s = psum32(psum16(s));
	v_mov_b32_e32 v146, v204
	v_mov_b32_e32 v147, v205
	v_mov_b32_e32 v148, v206
	v_mov_b32_e32 v149, v207
	v_mov_b32_dpp v204, v208 row_ror:8 row_mask:0xf bank_mask:0xc
	v_mov_b32_dpp v205, v209 row_ror:8 row_mask:0xf bank_mask:0xc
	v_mov_b32_dpp v206, v210 row_ror:8 row_mask:0xf bank_mask:0xc
	v_mov_b32_dpp v207, v211 row_ror:8 row_mask:0xf bank_mask:0xc
	v_mov_b32_dpp v208, v146 row_ror:8 row_mask:0xf bank_mask:0x3
	v_mov_b32_dpp v209, v147 row_ror:8 row_mask:0xf bank_mask:0x3
	v_mov_b32_dpp v210, v148 row_ror:8 row_mask:0xf bank_mask:0x3
	v_mov_b32_dpp v211, v149 row_ror:8 row_mask:0xf bank_mask:0x3
	v_lshlrev_b32_e32 v170, 16, v204
	v_and_b32_e32 v171, 0xffff0000, v204
	v_lshlrev_b32_e32 v172, 16, v205
	v_and_b32_e32 v173, 0xffff0000, v205
	v_lshlrev_b32_e32 v174, 16, v206
	v_and_b32_e32 v175, 0xffff0000, v206
	v_lshlrev_b32_e32 v176, 16, v207
	v_and_b32_e32 v177, 0xffff0000, v207
	v_pk_add_f32 v[124:125], v[124:125], v[170:171]
	v_pk_add_f32 v[126:127], v[126:127], v[172:173]
	v_pk_add_f32 v[120:121], v[120:121], v[174:175]
	v_pk_add_f32 v[122:123], v[122:123], v[176:177]
	v_cvt_pk_bf16_f32 v204, v124, v125
	v_cvt_pk_bf16_f32 v205, v126, v127
	v_cvt_pk_bf16_f32 v206, v120, v121
	v_cvt_pk_bf16_f32 v207, v122, v123
	v_mul_f32_e32 v178, v124, v124
	v_fmac_f32_e32 v178, v125, v125
	v_fmac_f32_e32 v178, v126, v126
	v_fmac_f32_e32 v178, v127, v127
	v_fmac_f32_e32 v178, v120, v120
	v_fmac_f32_e32 v178, v121, v121
	v_fmac_f32_e32 v178, v122, v122
	v_fmac_f32_e32 v178, v123, v123
	v_lshlrev_b32_e32 v170, 16, v208
	v_and_b32_e32 v171, 0xffff0000, v208
	v_lshlrev_b32_e32 v172, 16, v209
	v_and_b32_e32 v173, 0xffff0000, v209
	v_lshlrev_b32_e32 v174, 16, v210
	v_and_b32_e32 v175, 0xffff0000, v210
	v_lshlrev_b32_e32 v176, 16, v211
	v_and_b32_e32 v177, 0xffff0000, v211
	v_pk_add_f32 v[116:117], v[116:117], v[170:171]
	v_pk_add_f32 v[118:119], v[118:119], v[172:173]
	v_pk_add_f32 v[112:113], v[112:113], v[174:175]
	v_pk_add_f32 v[114:115], v[114:115], v[176:177]
	v_cvt_pk_bf16_f32 v208, v116, v117
	v_cvt_pk_bf16_f32 v209, v118, v119
	v_cvt_pk_bf16_f32 v210, v112, v113
	v_cvt_pk_bf16_f32 v211, v114, v115
	v_fmac_f32_e32 v178, v116, v116
	v_fmac_f32_e32 v178, v117, v117
	v_fmac_f32_e32 v178, v118, v118
	v_fmac_f32_e32 v178, v119, v119
	v_fmac_f32_e32 v178, v112, v112
	v_fmac_f32_e32 v178, v113, v113
	v_fmac_f32_e32 v178, v114, v114
	v_fmac_f32_e32 v178, v115, v115
	v_mov_b32_e32 v146, v204
	v_mov_b32_e32 v147, v205
	v_mov_b32_e32 v148, v206
	v_mov_b32_e32 v149, v207
	v_mov_b32_dpp v204, v208 row_ror:8 row_mask:0xf bank_mask:0xc
	v_mov_b32_dpp v205, v209 row_ror:8 row_mask:0xf bank_mask:0xc
	v_mov_b32_dpp v206, v210 row_ror:8 row_mask:0xf bank_mask:0xc
	v_mov_b32_dpp v207, v211 row_ror:8 row_mask:0xf bank_mask:0xc
	v_mov_b32_dpp v208, v146 row_ror:8 row_mask:0xf bank_mask:0x3
	v_mov_b32_dpp v209, v147 row_ror:8 row_mask:0xf bank_mask:0x3
	v_mov_b32_dpp v210, v148 row_ror:8 row_mask:0xf bank_mask:0x3
	v_mov_b32_dpp v211, v149 row_ror:8 row_mask:0xf bank_mask:0x3
	v_mov_b32_e32 v179, v178
	s_nop 1
	v_permlane16_swap_b32_e32 v178, v179
	v_add_f32_e32 v178, v178, v179
	v_mov_b32_e32 v179, v178
	s_nop 1
	v_permlane32_swap_b32_e32 v178, v179
	v_add_f32_e32 v180, v178, v179
	s_waitcnt vmcnt(12)
	v_mov_b32_e32 v146, v212
	v_mov_b32_e32 v147, v213
	v_mov_b32_e32 v148, v214
	v_mov_b32_e32 v149, v215
	v_mov_b32_dpp v212, v216 row_ror:8 row_mask:0xf bank_mask:0xc
	v_mov_b32_dpp v213, v217 row_ror:8 row_mask:0xf bank_mask:0xc
	v_mov_b32_dpp v214, v218 row_ror:8 row_mask:0xf bank_mask:0xc
	v_mov_b32_dpp v215, v219 row_ror:8 row_mask:0xf bank_mask:0xc
	v_mov_b32_dpp v216, v146 row_ror:8 row_mask:0xf bank_mask:0x3
	v_mov_b32_dpp v217, v147 row_ror:8 row_mask:0xf bank_mask:0x3
	v_mov_b32_dpp v218, v148 row_ror:8 row_mask:0xf bank_mask:0x3
	v_mov_b32_dpp v219, v149 row_ror:8 row_mask:0xf bank_mask:0x3
	v_lshlrev_b32_e32 v170, 16, v212
	v_and_b32_e32 v171, 0xffff0000, v212
	v_lshlrev_b32_e32 v172, 16, v213
	v_and_b32_e32 v173, 0xffff0000, v213
	v_lshlrev_b32_e32 v174, 16, v214
	v_and_b32_e32 v175, 0xffff0000, v214
	v_lshlrev_b32_e32 v176, 16, v215
	v_and_b32_e32 v177, 0xffff0000, v215
	v_pk_add_f32 v[108:109], v[108:109], v[170:171]
	v_pk_add_f32 v[110:111], v[110:111], v[172:173]
	v_pk_add_f32 v[104:105], v[104:105], v[174:175]
	v_pk_add_f32 v[106:107], v[106:107], v[176:177]
	v_cvt_pk_bf16_f32 v212, v108, v109
	v_cvt_pk_bf16_f32 v213, v110, v111
	v_cvt_pk_bf16_f32 v214, v104, v105
	v_cvt_pk_bf16_f32 v215, v106, v107
	v_mul_f32_e32 v178, v108, v108
	v_fmac_f32_e32 v178, v109, v109
	v_fmac_f32_e32 v178, v110, v110
	v_fmac_f32_e32 v178, v111, v111
	v_fmac_f32_e32 v178, v104, v104
	v_fmac_f32_e32 v178, v105, v105
	v_fmac_f32_e32 v178, v106, v106
	v_fmac_f32_e32 v178, v107, v107
	v_lshlrev_b32_e32 v170, 16, v216
	v_and_b32_e32 v171, 0xffff0000, v216
	v_lshlrev_b32_e32 v172, 16, v217
	v_and_b32_e32 v173, 0xffff0000, v217
	v_lshlrev_b32_e32 v174, 16, v218
	v_and_b32_e32 v175, 0xffff0000, v218
	v_lshlrev_b32_e32 v176, 16, v219
	v_and_b32_e32 v177, 0xffff0000, v219
	v_pk_add_f32 v[100:101], v[100:101], v[170:171]
	v_pk_add_f32 v[102:103], v[102:103], v[172:173]
	v_pk_add_f32 v[96:97], v[96:97], v[174:175]
	v_pk_add_f32 v[98:99], v[98:99], v[176:177]
	v_cvt_pk_bf16_f32 v216, v100, v101
	v_cvt_pk_bf16_f32 v217, v102, v103
	v_cvt_pk_bf16_f32 v218, v96, v97
	v_cvt_pk_bf16_f32 v219, v98, v99
	v_fmac_f32_e32 v178, v100, v100
	v_fmac_f32_e32 v178, v101, v101
	v_fmac_f32_e32 v178, v102, v102
	v_fmac_f32_e32 v178, v103, v103
	v_fmac_f32_e32 v178, v96, v96
	v_fmac_f32_e32 v178, v97, v97
	v_fmac_f32_e32 v178, v98, v98
	v_fmac_f32_e32 v178, v99, v99
	v_mov_b32_e32 v146, v212
	v_mov_b32_e32 v147, v213
	v_mov_b32_e32 v148, v214
	v_mov_b32_e32 v149, v215
	v_mov_b32_dpp v212, v216 row_ror:8 row_mask:0xf bank_mask:0xc
	v_mov_b32_dpp v213, v217 row_ror:8 row_mask:0xf bank_mask:0xc
	v_mov_b32_dpp v214, v218 row_ror:8 row_mask:0xf bank_mask:0xc
	v_mov_b32_dpp v215, v219 row_ror:8 row_mask:0xf bank_mask:0xc
	v_mov_b32_dpp v216, v146 row_ror:8 row_mask:0xf bank_mask:0x3
	v_mov_b32_dpp v217, v147 row_ror:8 row_mask:0xf bank_mask:0x3
	v_mov_b32_dpp v218, v148 row_ror:8 row_mask:0xf bank_mask:0x3
	v_mov_b32_dpp v219, v149 row_ror:8 row_mask:0xf bank_mask:0x3
	v_mov_b32_e32 v179, v178
	s_nop 1
	v_permlane16_swap_b32_e32 v178, v179
	v_add_f32_e32 v178, v178, v179
	v_mov_b32_e32 v179, v178
	s_nop 1
	v_permlane32_swap_b32_e32 v178, v179
	v_add_f32_e32 v181, v178, v179
	s_waitcnt vmcnt(10)
; __device__ __forceinline__ float bflo(unsigned w) { return __uint_as_float(w << 16); }
; __device__ __forceinline__ float bfhi(unsigned w) { return __uint_as_float(w & 0xffff0000u); }
; __device__ __forceinline__ u32x4 pack8(f32x4 a, f32x4 b) { u32x4 w; w[0] = cvt_pk_bf16(a[0], a[1]); w[1] = cvt_pk_bf16(a[2], a[3]); w[2] = cvt_pk_bf16(b[0], b[1]); w[3] = cvt_pk_bf16(b[2], b[3]); return w; }
; __device__ __forceinline__ float psum16(float x) { const u32x2s r = __builtin_amdgcn_permlane16_swap(__float_as_uint(x), __float_as_uint(x), false, false); return __uint_as_float(r[0]) + __uint_as_float(r[1]); }
; __device__ __forceinline__ float psum32(float x) { const u32x2s r = __builtin_amdgcn_permlane32_swap(__float_as_uint(x), __float_as_uint(x), false, false); return __uint_as_float(r[0]) + __uint_as_float(r[1]); }
;   __device__ __forceinline__ void operator()(const Acc& acc, const GUnit& u, int wr, int wc, int fr, int fq) const {
;     ...
;         const int row = row0 + ai * 128 + m * 16; const size_t off = (size_t)row * 2048 + col0; float s = 0.f;
; #pragma unroll
;         for (int bj = 0; bj < 2; ++bj) {
;           f32x4 r0, r1;
;           if (R) { r0 = *(const f32x4*)(R + off + bj * 128); r1 = *(const f32x4*)(R + off + bj * 128 + 4); }
;           else { const u32x4 rw = *(const u32x4*)(RB + (size_t)row * ldrb + col0 + bj * 128);
;             r0 = (f32x4){bflo(rw[0]), bfhi(rw[0]), bflo(rw[1]), bfhi(rw[1])}; r1 = (f32x4){bflo(rw[2]), bfhi(rw[2]), bflo(rw[3]), bfhi(rw[3])}; }
;           const f32x4 h0 = r0 + acc[ai][bj][m][0] * osc, h1 = r1 + acc[ai][bj][m][1] * osc;
;           if (H) { *(f32x4*)(H + off + bj * 128) = h0; *(f32x4*)(H + off + bj * 128 + 4) = h1; }
;           if (HB) *(u32x4*)(HB + (size_t)row * ldhb + col0 + bj * 128) = pack8(h0, h1);
;           s += h0[0] * h0[0] + h0[1] * h0[1] + h0[2] * h0[2] + h0[3] * h0[3] + h1[0] * h1[0] + h1[1] * h1[1] + h1[2] * h1[2] + h1[3] * h1[3];
;         }
;         s = psum32(psum16(s));
	v_mov_b32_e32 v146, v220
	v_mov_b32_e32 v147, v221
	v_mov_b32_e32 v148, v222
	v_mov_b32_e32 v149, v223
	v_mov_b32_dpp v220, v224 row_ror:8 row_mask:0xf bank_mask:0xc
	v_mov_b32_dpp v221, v225 row_ror:8 row_mask:0xf bank_mask:0xc
	v_mov_b32_dpp v222, v226 row_ror:8 row_mask:0xf bank_mask:0xc
	v_mov_b32_dpp v223, v227 row_ror:8 row_mask:0xf bank_mask:0xc
	v_mov_b32_dpp v224, v146 row_ror:8 row_mask:0xf bank_mask:0x3
	v_mov_b32_dpp v225, v147 row_ror:8 row_mask:0xf bank_mask:0x3
	v_mov_b32_dpp v226, v148 row_ror:8 row_mask:0xf bank_mask:0x3
	v_mov_b32_dpp v227, v149 row_ror:8 row_mask:0xf bank_mask:0x3
	v_lshlrev_b32_e32 v170, 16, v220
	v_and_b32_e32 v171, 0xffff0000, v220
	v_lshlrev_b32_e32 v172, 16, v221
	v_and_b32_e32 v173, 0xffff0000, v221
	v_lshlrev_b32_e32 v174, 16, v222
	v_and_b32_e32 v175, 0xffff0000, v222
	v_lshlrev_b32_e32 v176, 16, v223
	v_and_b32_e32 v177, 0xffff0000, v223
	v_pk_add_f32 v[92:93], v[92:93], v[170:171]
	v_pk_add_f32 v[94:95], v[94:95], v[172:173]
	v_pk_add_f32 v[88:89], v[88:89], v[174:175]
	v_pk_add_f32 v[90:91], v[90:91], v[176:177]
	v_cvt_pk_bf16_f32 v220, v92, v93
	v_cvt_pk_bf16_f32 v221, v94, v95
	v_cvt_pk_bf16_f32 v222, v88, v89
	v_cvt_pk_bf16_f32 v223, v90, v91
	v_mul_f32_e32 v178, v92, v92
	v_fmac_f32_e32 v178, v93, v93
	v_fmac_f32_e32 v178, v94, v94
	v_fmac_f32_e32 v178, v95, v95
	v_fmac_f32_e32 v178, v88, v88
	v_fmac_f32_e32 v178, v89, v89
	v_fmac_f32_e32 v178, v90, v90
	v_fmac_f32_e32 v178, v91, v91
	v_lshlrev_b32_e32 v170, 16, v224
	v_and_b32_e32 v171, 0xffff0000, v224
	v_lshlrev_b32_e32 v172, 16, v225
	v_and_b32_e32 v173, 0xffff0000, v225
	v_lshlrev_b32_e32 v174, 16, v226
	v_and_b32_e32 v175, 0xffff0000, v226
	v_lshlrev_b32_e32 v176, 16, v227
	v_and_b32_e32 v177, 0xffff0000, v227
	v_pk_add_f32 v[84:85], v[84:85], v[170:171]
	v_pk_add_f32 v[86:87], v[86:87], v[172:173]
	v_pk_add_f32 v[80:81], v[80:81], v[174:175]
	v_pk_add_f32 v[82:83], v[82:83], v[176:177]
	v_cvt_pk_bf16_f32 v224, v84, v85
	v_cvt_pk_bf16_f32 v225, v86, v87
	v_cvt_pk_bf16_f32 v226, v80, v81
	v_cvt_pk_bf16_f32 v227, v82, v83
	v_fmac_f32_e32 v178, v84, v84
	v_fmac_f32_e32 v178, v85, v85
	v_fmac_f32_e32 v178, v86, v86
	v_fmac_f32_e32 v178, v87, v87
	v_fmac_f32_e32 v178, v80, v80
	v_fmac_f32_e32 v178, v81, v81
	v_fmac_f32_e32 v178, v82, v82
	v_fmac_f32_e32 v178, v83, v83
	v_mov_b32_e32 v146, v220
	v_mov_b32_e32 v147, v221
	v_mov_b32_e32 v148, v222
	v_mov_b32_e32 v149, v223
	v_mov_b32_dpp v220, v224 row_ror:8 row_mask:0xf bank_mask:0xc
	v_mov_b32_dpp v221, v225 row_ror:8 row_mask:0xf bank_mask:0xc
	v_mov_b32_dpp v222, v226 row_ror:8 row_mask:0xf bank_mask:0xc
	v_mov_b32_dpp v223, v227 row_ror:8 row_mask:0xf bank_mask:0xc
	v_mov_b32_dpp v224, v146 row_ror:8 row_mask:0xf bank_mask:0x3
	v_mov_b32_dpp v225, v147 row_ror:8 row_mask:0xf bank_mask:0x3
	v_mov_b32_dpp v226, v148 row_ror:8 row_mask:0xf bank_mask:0x3
	v_mov_b32_dpp v227, v149 row_ror:8 row_mask:0xf bank_mask:0x3
	v_mov_b32_e32 v179, v178
	s_nop 1
	v_permlane16_swap_b32_e32 v178, v179
	v_add_f32_e32 v178, v178, v179
	v_mov_b32_e32 v179, v178
	s_nop 1
	v_permlane32_swap_b32_e32 v178, v179
	v_add_f32_e32 v182, v178, v179
	s_waitcnt vmcnt(8)
	v_mov_b32_e32 v146, v228
	v_mov_b32_e32 v147, v229
	v_mov_b32_e32 v148, v230
	v_mov_b32_e32 v149, v231
	v_mov_b32_dpp v228, v232 row_ror:8 row_mask:0xf bank_mask:0xc
	v_mov_b32_dpp v229, v233 row_ror:8 row_mask:0xf bank_mask:0xc
	v_mov_b32_dpp v230, v234 row_ror:8 row_mask:0xf bank_mask:0xc
	v_mov_b32_dpp v231, v235 row_ror:8 row_mask:0xf bank_mask:0xc
	v_mov_b32_dpp v232, v146 row_ror:8 row_mask:0xf bank_mask:0x3
	v_mov_b32_dpp v233, v147 row_ror:8 row_mask:0xf bank_mask:0x3
	v_mov_b32_dpp v234, v148 row_ror:8 row_mask:0xf bank_mask:0x3
	v_mov_b32_dpp v235, v149 row_ror:8 row_mask:0xf bank_mask:0x3
	v_lshlrev_b32_e32 v170, 16, v228
	v_and_b32_e32 v171, 0xffff0000, v228
	v_lshlrev_b32_e32 v172, 16, v229
	v_and_b32_e32 v173, 0xffff0000, v229
	v_lshlrev_b32_e32 v174, 16, v230
	v_and_b32_e32 v175, 0xffff0000, v230
	v_lshlrev_b32_e32 v176, 16, v231
	v_and_b32_e32 v177, 0xffff0000, v231
	v_pk_add_f32 v[76:77], v[76:77], v[170:171]
	v_pk_add_f32 v[78:79], v[78:79], v[172:173]
	v_pk_add_f32 v[72:73], v[72:73], v[174:175]
	v_pk_add_f32 v[74:75], v[74:75], v[176:177]
	v_cvt_pk_bf16_f32 v228, v76, v77
	v_cvt_pk_bf16_f32 v229, v78, v79
	v_cvt_pk_bf16_f32 v230, v72, v73
	v_cvt_pk_bf16_f32 v231, v74, v75
	v_mul_f32_e32 v178, v76, v76
	v_fmac_f32_e32 v178, v77, v77
	v_fmac_f32_e32 v178, v78, v78
	v_fmac_f32_e32 v178, v79, v79
	v_fmac_f32_e32 v178, v72, v72
	v_fmac_f32_e32 v178, v73, v73
	v_fmac_f32_e32 v178, v74, v74
	v_fmac_f32_e32 v178, v75, v75
	v_lshlrev_b32_e32 v170, 16, v232
	v_and_b32_e32 v171, 0xffff0000, v232
	v_lshlrev_b32_e32 v172, 16, v233
	v_and_b32_e32 v173, 0xffff0000, v233
	v_lshlrev_b32_e32 v174, 16, v234
	v_and_b32_e32 v175, 0xffff0000, v234
	v_lshlrev_b32_e32 v176, 16, v235
	v_and_b32_e32 v177, 0xffff0000, v235
	v_pk_add_f32 v[68:69], v[68:69], v[170:171]
	v_pk_add_f32 v[70:71], v[70:71], v[172:173]
	v_pk_add_f32 v[64:65], v[64:65], v[174:175]
	v_pk_add_f32 v[66:67], v[66:67], v[176:177]
	v_cvt_pk_bf16_f32 v232, v68, v69
	v_cvt_pk_bf16_f32 v233, v70, v71
	v_cvt_pk_bf16_f32 v234, v64, v65
	v_cvt_pk_bf16_f32 v235, v66, v67
	v_fmac_f32_e32 v178, v68, v68
	v_fmac_f32_e32 v178, v69, v69
	v_fmac_f32_e32 v178, v70, v70
	v_fmac_f32_e32 v178, v71, v71
	v_fmac_f32_e32 v178, v64, v64
	v_fmac_f32_e32 v178, v65, v65
	v_fmac_f32_e32 v178, v66, v66
	v_fmac_f32_e32 v178, v67, v67
	v_mov_b32_e32 v146, v228
	v_mov_b32_e32 v147, v229
	v_mov_b32_e32 v148, v230
	v_mov_b32_e32 v149, v231
	v_mov_b32_dpp v228, v232 row_ror:8 row_mask:0xf bank_mask:0xc
	v_mov_b32_dpp v229, v233 row_ror:8 row_mask:0xf bank_mask:0xc
	v_mov_b32_dpp v230, v234 row_ror:8 row_mask:0xf bank_mask:0xc
	v_mov_b32_dpp v231, v235 row_ror:8 row_mask:0xf bank_mask:0xc
	v_mov_b32_dpp v232, v146 row_ror:8 row_mask:0xf bank_mask:0x3
	v_mov_b32_dpp v233, v147 row_ror:8 row_mask:0xf bank_mask:0x3
	v_mov_b32_dpp v234, v148 row_ror:8 row_mask:0xf bank_mask:0x3
	v_mov_b32_dpp v235, v149 row_ror:8 row_mask:0xf bank_mask:0x3
	v_mov_b32_e32 v179, v178
	s_nop 1
	v_permlane16_swap_b32_e32 v178, v179
	v_add_f32_e32 v178, v178, v179
	v_mov_b32_e32 v179, v178
	s_nop 1
	v_permlane32_swap_b32_e32 v178, v179
	v_add_f32_e32 v183, v178, v179
	s_waitcnt vmcnt(6)
; __device__ __forceinline__ float bflo(unsigned w) { return __uint_as_float(w << 16); }
; __device__ __forceinline__ float bfhi(unsigned w) { return __uint_as_float(w & 0xffff0000u); }
; __device__ __forceinline__ u32x4 pack8(f32x4 a, f32x4 b) { u32x4 w; w[0] = cvt_pk_bf16(a[0], a[1]); w[1] = cvt_pk_bf16(a[2], a[3]); w[2] = cvt_pk_bf16(b[0], b[1]); w[3] = cvt_pk_bf16(b[2], b[3]); return w; }
; __device__ __forceinline__ float psum16(float x) { const u32x2s r = __builtin_amdgcn_permlane16_swap(__float_as_uint(x), __float_as_uint(x), false, false); return __uint_as_float(r[0]) + __uint_as_float(r[1]); }
; __device__ __forceinline__ float psum32(float x) { const u32x2s r = __builtin_amdgcn_permlane32_swap(__float_as_uint(x), __float_as_uint(x), false, false); return __uint_as_float(r[0]) + __uint_as_float(r[1]); }
;   __device__ __forceinline__ void operator()(const Acc& acc, const GUnit& u, int wr, int wc, int fr, int fq) const {
;     ...
;         const int row = row0 + ai * 128 + m * 16; const size_t off = (size_t)row * 2048 + col0; float s = 0.f;
; #pragma unroll
;         for (int bj = 0; bj < 2; ++bj) {
;           f32x4 r0, r1;
;           if (R) { r0 = *(const f32x4*)(R + off + bj * 128); r1 = *(const f32x4*)(R + off + bj * 128 + 4); }
;           else { const u32x4 rw = *(const u32x4*)(RB + (size_t)row * ldrb + col0 + bj * 128);
;             r0 = (f32x4){bflo(rw[0]), bfhi(rw[0]), bflo(rw[1]), bfhi(rw[1])}; r1 = (f32x4){bflo(rw[2]), bfhi(rw[2]), bflo(rw[3]), bfhi(rw[3])}; }
;           const f32x4 h0 = r0 + acc[ai][bj][m][0] * osc, h1 = r1 + acc[ai][bj][m][1] * osc;
;           if (H) { *(f32x4*)(H + off + bj * 128) = h0; *(f32x4*)(H + off + bj * 128 + 4) = h1; }
;           if (HB) *(u32x4*)(HB + (size_t)row * ldhb + col0 + bj * 128) = pack8(h0, h1);
;           s += h0[0] * h0[0] + h0[1] * h0[1] + h0[2] * h0[2] + h0[3] * h0[3] + h1[0] * h1[0] + h1[1] * h1[1] + h1[2] * h1[2] + h1[3] * h1[3];
;         }
;         s = psum32(psum16(s));
	v_mov_b32_e32 v146, v236
	v_mov_b32_e32 v147, v237
	v_mov_b32_e32 v148, v238
	v_mov_b32_e32 v149, v239
	v_mov_b32_dpp v236, v240 row_ror:8 row_mask:0xf bank_mask:0xc
	v_mov_b32_dpp v237, v241 row_ror:8 row_mask:0xf bank_mask:0xc
	v_mov_b32_dpp v238, v242 row_ror:8 row_mask:0xf bank_mask:0xc
	v_mov_b32_dpp v239, v243 row_ror:8 row_mask:0xf bank_mask:0xc
	v_mov_b32_dpp v240, v146 row_ror:8 row_mask:0xf bank_mask:0x3
	v_mov_b32_dpp v241, v147 row_ror:8 row_mask:0xf bank_mask:0x3
	v_mov_b32_dpp v242, v148 row_ror:8 row_mask:0xf bank_mask:0x3
	v_mov_b32_dpp v243, v149 row_ror:8 row_mask:0xf bank_mask:0x3
	v_lshlrev_b32_e32 v170, 16, v236
	v_and_b32_e32 v171, 0xffff0000, v236
	v_lshlrev_b32_e32 v172, 16, v237
	v_and_b32_e32 v173, 0xffff0000, v237
	v_lshlrev_b32_e32 v174, 16, v238
	v_and_b32_e32 v175, 0xffff0000, v238
	v_lshlrev_b32_e32 v176, 16, v239
	v_and_b32_e32 v177, 0xffff0000, v239
	v_pk_add_f32 v[60:61], v[60:61], v[170:171]
	v_pk_add_f32 v[62:63], v[62:63], v[172:173]
	v_pk_add_f32 v[56:57], v[56:57], v[174:175]
	v_pk_add_f32 v[58:59], v[58:59], v[176:177]
	v_cvt_pk_bf16_f32 v236, v60, v61
	v_cvt_pk_bf16_f32 v237, v62, v63
	v_cvt_pk_bf16_f32 v238, v56, v57
	v_cvt_pk_bf16_f32 v239, v58, v59
	v_mul_f32_e32 v178, v60, v60
	v_fmac_f32_e32 v178, v61, v61
	v_fmac_f32_e32 v178, v62, v62
	v_fmac_f32_e32 v178, v63, v63
	v_fmac_f32_e32 v178, v56, v56
	v_fmac_f32_e32 v178, v57, v57
	v_fmac_f32_e32 v178, v58, v58
	v_fmac_f32_e32 v178, v59, v59
	v_lshlrev_b32_e32 v170, 16, v240
	v_and_b32_e32 v171, 0xffff0000, v240
	v_lshlrev_b32_e32 v172, 16, v241
	v_and_b32_e32 v173, 0xffff0000, v241
	v_lshlrev_b32_e32 v174, 16, v242
	v_and_b32_e32 v175, 0xffff0000, v242
	v_lshlrev_b32_e32 v176, 16, v243
	v_and_b32_e32 v177, 0xffff0000, v243
	v_pk_add_f32 v[52:53], v[52:53], v[170:171]
	v_pk_add_f32 v[54:55], v[54:55], v[172:173]
	v_pk_add_f32 v[48:49], v[48:49], v[174:175]
	v_pk_add_f32 v[50:51], v[50:51], v[176:177]
	v_cvt_pk_bf16_f32 v240, v52, v53
	v_cvt_pk_bf16_f32 v241, v54, v55
	v_cvt_pk_bf16_f32 v242, v48, v49
	v_cvt_pk_bf16_f32 v243, v50, v51
	v_fmac_f32_e32 v178, v52, v52
	v_fmac_f32_e32 v178, v53, v53
	v_fmac_f32_e32 v178, v54, v54
	v_fmac_f32_e32 v178, v55, v55
	v_fmac_f32_e32 v178, v48, v48
	v_fmac_f32_e32 v178, v49, v49
	v_fmac_f32_e32 v178, v50, v50
	v_fmac_f32_e32 v178, v51, v51
	v_mov_b32_e32 v146, v236
	v_mov_b32_e32 v147, v237
	v_mov_b32_e32 v148, v238
	v_mov_b32_e32 v149, v239
	v_mov_b32_dpp v236, v240 row_ror:8 row_mask:0xf bank_mask:0xc
	v_mov_b32_dpp v237, v241 row_ror:8 row_mask:0xf bank_mask:0xc
	v_mov_b32_dpp v238, v242 row_ror:8 row_mask:0xf bank_mask:0xc
	v_mov_b32_dpp v239, v243 row_ror:8 row_mask:0xf bank_mask:0xc
	v_mov_b32_dpp v240, v146 row_ror:8 row_mask:0xf bank_mask:0x3
	v_mov_b32_dpp v241, v147 row_ror:8 row_mask:0xf bank_mask:0x3
	v_mov_b32_dpp v242, v148 row_ror:8 row_mask:0xf bank_mask:0x3
	v_mov_b32_dpp v243, v149 row_ror:8 row_mask:0xf bank_mask:0x3
	v_mov_b32_e32 v179, v178
	s_nop 1
	v_permlane16_swap_b32_e32 v178, v179
	v_add_f32_e32 v178, v178, v179
	v_mov_b32_e32 v179, v178
	s_nop 1
	v_permlane32_swap_b32_e32 v178, v179
	v_add_f32_e32 v184, v178, v179
	s_waitcnt vmcnt(4)
	v_mov_b32_e32 v146, v244
	v_mov_b32_e32 v147, v245
	v_mov_b32_e32 v148, v246
	v_mov_b32_e32 v149, v247
	v_mov_b32_dpp v244, v248 row_ror:8 row_mask:0xf bank_mask:0xc
	v_mov_b32_dpp v245, v249 row_ror:8 row_mask:0xf bank_mask:0xc
	v_mov_b32_dpp v246, v250 row_ror:8 row_mask:0xf bank_mask:0xc
	v_mov_b32_dpp v247, v251 row_ror:8 row_mask:0xf bank_mask:0xc
	v_mov_b32_dpp v248, v146 row_ror:8 row_mask:0xf bank_mask:0x3
	v_mov_b32_dpp v249, v147 row_ror:8 row_mask:0xf bank_mask:0x3
	v_mov_b32_dpp v250, v148 row_ror:8 row_mask:0xf bank_mask:0x3
	v_mov_b32_dpp v251, v149 row_ror:8 row_mask:0xf bank_mask:0x3
	v_lshlrev_b32_e32 v170, 16, v244
	v_and_b32_e32 v171, 0xffff0000, v244
	v_lshlrev_b32_e32 v172, 16, v245
	v_and_b32_e32 v173, 0xffff0000, v245
	v_lshlrev_b32_e32 v174, 16, v246
	v_and_b32_e32 v175, 0xffff0000, v246
	v_lshlrev_b32_e32 v176, 16, v247
	v_and_b32_e32 v177, 0xffff0000, v247
	v_pk_add_f32 v[44:45], v[44:45], v[170:171]
	v_pk_add_f32 v[46:47], v[46:47], v[172:173]
	v_pk_add_f32 v[40:41], v[40:41], v[174:175]
	v_pk_add_f32 v[42:43], v[42:43], v[176:177]
	v_cvt_pk_bf16_f32 v244, v44, v45
	v_cvt_pk_bf16_f32 v245, v46, v47
	v_cvt_pk_bf16_f32 v246, v40, v41
	v_cvt_pk_bf16_f32 v247, v42, v43
	v_mul_f32_e32 v178, v44, v44
	v_fmac_f32_e32 v178, v45, v45
	v_fmac_f32_e32 v178, v46, v46
	v_fmac_f32_e32 v178, v47, v47
	v_fmac_f32_e32 v178, v40, v40
	v_fmac_f32_e32 v178, v41, v41
	v_fmac_f32_e32 v178, v42, v42
	v_fmac_f32_e32 v178, v43, v43
	v_lshlrev_b32_e32 v170, 16, v248
	v_and_b32_e32 v171, 0xffff0000, v248
	v_lshlrev_b32_e32 v172, 16, v249
	v_and_b32_e32 v173, 0xffff0000, v249
	v_lshlrev_b32_e32 v174, 16, v250
	v_and_b32_e32 v175, 0xffff0000, v250
	v_lshlrev_b32_e32 v176, 16, v251
	v_and_b32_e32 v177, 0xffff0000, v251
	v_pk_add_f32 v[36:37], v[36:37], v[170:171]
	v_pk_add_f32 v[38:39], v[38:39], v[172:173]
	v_pk_add_f32 v[32:33], v[32:33], v[174:175]
	v_pk_add_f32 v[34:35], v[34:35], v[176:177]
	v_cvt_pk_bf16_f32 v248, v36, v37
	v_cvt_pk_bf16_f32 v249, v38, v39
	v_cvt_pk_bf16_f32 v250, v32, v33
	v_cvt_pk_bf16_f32 v251, v34, v35
	v_fmac_f32_e32 v178, v36, v36
	v_fmac_f32_e32 v178, v37, v37
	v_fmac_f32_e32 v178, v38, v38
	v_fmac_f32_e32 v178, v39, v39
	v_fmac_f32_e32 v178, v32, v32
	v_fmac_f32_e32 v178, v33, v33
	v_fmac_f32_e32 v178, v34, v34
	v_fmac_f32_e32 v178, v35, v35
	v_mov_b32_e32 v146, v244
	v_mov_b32_e32 v147, v245
	v_mov_b32_e32 v148, v246
	v_mov_b32_e32 v149, v247
	v_mov_b32_dpp v244, v248 row_ror:8 row_mask:0xf bank_mask:0xc
	v_mov_b32_dpp v245, v249 row_ror:8 row_mask:0xf bank_mask:0xc
	v_mov_b32_dpp v246, v250 row_ror:8 row_mask:0xf bank_mask:0xc
	v_mov_b32_dpp v247, v251 row_ror:8 row_mask:0xf bank_mask:0xc
	v_mov_b32_dpp v248, v146 row_ror:8 row_mask:0xf bank_mask:0x3
	v_mov_b32_dpp v249, v147 row_ror:8 row_mask:0xf bank_mask:0x3
	v_mov_b32_dpp v250, v148 row_ror:8 row_mask:0xf bank_mask:0x3
	v_mov_b32_dpp v251, v149 row_ror:8 row_mask:0xf bank_mask:0x3
	v_mov_b32_e32 v179, v178
	s_nop 1
	v_permlane16_swap_b32_e32 v178, v179
	v_add_f32_e32 v178, v178, v179
	v_mov_b32_e32 v179, v178
	s_nop 1
	v_permlane32_swap_b32_e32 v178, v179
	v_add_f32_e32 v185, v178, v179
	s_waitcnt vmcnt(2)
; __device__ __forceinline__ float bflo(unsigned w) { return __uint_as_float(w << 16); }
; __device__ __forceinline__ float bfhi(unsigned w) { return __uint_as_float(w & 0xffff0000u); }
; __device__ __forceinline__ u32x4 pack8(f32x4 a, f32x4 b) { u32x4 w; w[0] = cvt_pk_bf16(a[0], a[1]); w[1] = cvt_pk_bf16(a[2], a[3]); w[2] = cvt_pk_bf16(b[0], b[1]); w[3] = cvt_pk_bf16(b[2], b[3]); return w; }
; __device__ __forceinline__ float psum16(float x) { const u32x2s r = __builtin_amdgcn_permlane16_swap(__float_as_uint(x), __float_as_uint(x), false, false); return __uint_as_float(r[0]) + __uint_as_float(r[1]); }
; __device__ __forceinline__ float psum32(float x) { const u32x2s r = __builtin_amdgcn_permlane32_swap(__float_as_uint(x), __float_as_uint(x), false, false); return __uint_as_float(r[0]) + __uint_as_float(r[1]); }
;   __device__ __forceinline__ void operator()(const Acc& acc, const GUnit& u, int wr, int wc, int fr, int fq) const {
;     ...
;         const int row = row0 + ai * 128 + m * 16; const size_t off = (size_t)row * 2048 + col0; float s = 0.f;
; #pragma unroll
;         for (int bj = 0; bj < 2; ++bj) {
;           f32x4 r0, r1;
;           if (R) { r0 = *(const f32x4*)(R + off + bj * 128); r1 = *(const f32x4*)(R + off + bj * 128 + 4); }
;           else { const u32x4 rw = *(const u32x4*)(RB + (size_t)row * ldrb + col0 + bj * 128);
;             r0 = (f32x4){bflo(rw[0]), bfhi(rw[0]), bflo(rw[1]), bfhi(rw[1])}; r1 = (f32x4){bflo(rw[2]), bfhi(rw[2]), bflo(rw[3]), bfhi(rw[3])}; }
;           const f32x4 h0 = r0 + acc[ai][bj][m][0] * osc, h1 = r1 + acc[ai][bj][m][1] * osc;
;           if (H) { *(f32x4*)(H + off + bj * 128) = h0; *(f32x4*)(H + off + bj * 128 + 4) = h1; }
;           if (HB) *(u32x4*)(HB + (size_t)row * ldhb + col0 + bj * 128) = pack8(h0, h1);
;           s += h0[0] * h0[0] + h0[1] * h0[1] + h0[2] * h0[2] + h0[3] * h0[3] + h1[0] * h1[0] + h1[1] * h1[1] + h1[2] * h1[2] + h1[3] * h1[3];
;         }
;         s = psum32(psum16(s));
	v_mov_b32_e32 v146, v154
	v_mov_b32_e32 v147, v155
	v_mov_b32_e32 v148, v156
	v_mov_b32_e32 v149, v157
	v_mov_b32_dpp v154, v158 row_ror:8 row_mask:0xf bank_mask:0xc
	v_mov_b32_dpp v155, v159 row_ror:8 row_mask:0xf bank_mask:0xc
	v_mov_b32_dpp v156, v160 row_ror:8 row_mask:0xf bank_mask:0xc
	v_mov_b32_dpp v157, v161 row_ror:8 row_mask:0xf bank_mask:0xc
	v_mov_b32_dpp v158, v146 row_ror:8 row_mask:0xf bank_mask:0x3
	v_mov_b32_dpp v159, v147 row_ror:8 row_mask:0xf bank_mask:0x3
	v_mov_b32_dpp v160, v148 row_ror:8 row_mask:0xf bank_mask:0x3
	v_mov_b32_dpp v161, v149 row_ror:8 row_mask:0xf bank_mask:0x3
	v_lshlrev_b32_e32 v170, 16, v154
	v_and_b32_e32 v171, 0xffff0000, v154
	v_lshlrev_b32_e32 v172, 16, v155
	v_and_b32_e32 v173, 0xffff0000, v155
	v_lshlrev_b32_e32 v174, 16, v156
	v_and_b32_e32 v175, 0xffff0000, v156
	v_lshlrev_b32_e32 v176, 16, v157
	v_and_b32_e32 v177, 0xffff0000, v157
	v_pk_add_f32 v[28:29], v[28:29], v[170:171]
	v_pk_add_f32 v[30:31], v[30:31], v[172:173]
	v_pk_add_f32 v[24:25], v[24:25], v[174:175]
	v_pk_add_f32 v[26:27], v[26:27], v[176:177]
	v_cvt_pk_bf16_f32 v154, v28, v29
	v_cvt_pk_bf16_f32 v155, v30, v31
	v_cvt_pk_bf16_f32 v156, v24, v25
	v_cvt_pk_bf16_f32 v157, v26, v27
	v_mul_f32_e32 v178, v28, v28
	v_fmac_f32_e32 v178, v29, v29
	v_fmac_f32_e32 v178, v30, v30
	v_fmac_f32_e32 v178, v31, v31
	v_fmac_f32_e32 v178, v24, v24
	v_fmac_f32_e32 v178, v25, v25
	v_fmac_f32_e32 v178, v26, v26
	v_fmac_f32_e32 v178, v27, v27
	v_lshlrev_b32_e32 v170, 16, v158
	v_and_b32_e32 v171, 0xffff0000, v158
	v_lshlrev_b32_e32 v172, 16, v159
	v_and_b32_e32 v173, 0xffff0000, v159
	v_lshlrev_b32_e32 v174, 16, v160
	v_and_b32_e32 v175, 0xffff0000, v160
	v_lshlrev_b32_e32 v176, 16, v161
	v_and_b32_e32 v177, 0xffff0000, v161
	v_pk_add_f32 v[20:21], v[20:21], v[170:171]
	v_pk_add_f32 v[22:23], v[22:23], v[172:173]
	v_pk_add_f32 v[16:17], v[16:17], v[174:175]
	v_pk_add_f32 v[18:19], v[18:19], v[176:177]
	v_cvt_pk_bf16_f32 v158, v20, v21
	v_cvt_pk_bf16_f32 v159, v22, v23
	v_cvt_pk_bf16_f32 v160, v16, v17
	v_cvt_pk_bf16_f32 v161, v18, v19
	v_fmac_f32_e32 v178, v20, v20
	v_fmac_f32_e32 v178, v21, v21
	v_fmac_f32_e32 v178, v22, v22
	v_fmac_f32_e32 v178, v23, v23
	v_fmac_f32_e32 v178, v16, v16
	v_fmac_f32_e32 v178, v17, v17
	v_fmac_f32_e32 v178, v18, v18
	v_fmac_f32_e32 v178, v19, v19
	v_mov_b32_e32 v146, v154
	v_mov_b32_e32 v147, v155
	v_mov_b32_e32 v148, v156
	v_mov_b32_e32 v149, v157
	v_mov_b32_dpp v154, v158 row_ror:8 row_mask:0xf bank_mask:0xc
	v_mov_b32_dpp v155, v159 row_ror:8 row_mask:0xf bank_mask:0xc
	v_mov_b32_dpp v156, v160 row_ror:8 row_mask:0xf bank_mask:0xc
	v_mov_b32_dpp v157, v161 row_ror:8 row_mask:0xf bank_mask:0xc
	v_mov_b32_dpp v158, v146 row_ror:8 row_mask:0xf bank_mask:0x3
	v_mov_b32_dpp v159, v147 row_ror:8 row_mask:0xf bank_mask:0x3
	v_mov_b32_dpp v160, v148 row_ror:8 row_mask:0xf bank_mask:0x3
	v_mov_b32_dpp v161, v149 row_ror:8 row_mask:0xf bank_mask:0x3
	v_mov_b32_e32 v179, v178
	s_nop 1
	v_permlane16_swap_b32_e32 v178, v179
	v_add_f32_e32 v178, v178, v179
	v_mov_b32_e32 v179, v178
	s_nop 1
	v_permlane32_swap_b32_e32 v178, v179
	v_add_f32_e32 v186, v178, v179
	s_waitcnt vmcnt(0)
; __device__ __forceinline__ float bflo(unsigned w) { return __uint_as_float(w << 16); }
; __device__ __forceinline__ float bfhi(unsigned w) { return __uint_as_float(w & 0xffff0000u); }
; __device__ __forceinline__ u32x4 pack8(f32x4 a, f32x4 b) { u32x4 w; w[0] = cvt_pk_bf16(a[0], a[1]); w[1] = cvt_pk_bf16(a[2], a[3]); w[2] = cvt_pk_bf16(b[0], b[1]); w[3] = cvt_pk_bf16(b[2], b[3]); return w; }
; __device__ __forceinline__ float psum16(float x) { const u32x2s r = __builtin_amdgcn_permlane16_swap(__float_as_uint(x), __float_as_uint(x), false, false); return __uint_as_float(r[0]) + __uint_as_float(r[1]); }
; __device__ __forceinline__ float psum32(float x) { const u32x2s r = __builtin_amdgcn_permlane32_swap(__float_as_uint(x), __float_as_uint(x), false, false); return __uint_as_float(r[0]) + __uint_as_float(r[1]); }
;   __device__ __forceinline__ void operator()(const Acc& acc, const GUnit& u, int wr, int wc, int fr, int fq) const {
;     ...
;         const int row = row0 + ai * 128 + m * 16; const size_t off = (size_t)row * 2048 + col0; float s = 0.f;
; #pragma unroll
;         for (int bj = 0; bj < 2; ++bj) {
;           f32x4 r0, r1;
;           if (R) { r0 = *(const f32x4*)(R + off + bj * 128); r1 = *(const f32x4*)(R + off + bj * 128 + 4); }
;           else { const u32x4 rw = *(const u32x4*)(RB + (size_t)row * ldrb + col0 + bj * 128);
;             r0 = (f32x4){bflo(rw[0]), bfhi(rw[0]), bflo(rw[1]), bfhi(rw[1])}; r1 = (f32x4){bflo(rw[2]), bfhi(rw[2]), bflo(rw[3]), bfhi(rw[3])}; }
;           const f32x4 h0 = r0 + acc[ai][bj][m][0] * osc, h1 = r1 + acc[ai][bj][m][1] * osc;
;           if (H) { *(f32x4*)(H + off + bj * 128) = h0; *(f32x4*)(H + off + bj * 128 + 4) = h1; }
;           if (HB) *(u32x4*)(HB + (size_t)row * ldhb + col0 + bj * 128) = pack8(h0, h1);
;           s += h0[0] * h0[0] + h0[1] * h0[1] + h0[2] * h0[2] + h0[3] * h0[3] + h1[0] * h1[0] + h1[1] * h1[1] + h1[2] * h1[2] + h1[3] * h1[3];
;         }
;         s = psum32(psum16(s));
;         if (fq == 0) atomicAdd(ss + row, s);
	v_mov_b32_e32 v146, v162
	v_mov_b32_e32 v147, v163
	v_mov_b32_e32 v148, v164
	v_mov_b32_e32 v149, v165
	v_mov_b32_dpp v162, v166 row_ror:8 row_mask:0xf bank_mask:0xc
	v_mov_b32_dpp v163, v167 row_ror:8 row_mask:0xf bank_mask:0xc
	v_mov_b32_dpp v164, v168 row_ror:8 row_mask:0xf bank_mask:0xc
	v_mov_b32_dpp v165, v169 row_ror:8 row_mask:0xf bank_mask:0xc
	v_mov_b32_dpp v166, v146 row_ror:8 row_mask:0xf bank_mask:0x3
	v_mov_b32_dpp v167, v147 row_ror:8 row_mask:0xf bank_mask:0x3
	v_mov_b32_dpp v168, v148 row_ror:8 row_mask:0xf bank_mask:0x3
	v_mov_b32_dpp v169, v149 row_ror:8 row_mask:0xf bank_mask:0x3
	v_lshlrev_b32_e32 v170, 16, v162
	v_and_b32_e32 v171, 0xffff0000, v162
	v_lshlrev_b32_e32 v172, 16, v163
	v_and_b32_e32 v173, 0xffff0000, v163
	v_lshlrev_b32_e32 v174, 16, v164
	v_and_b32_e32 v175, 0xffff0000, v164
	v_lshlrev_b32_e32 v176, 16, v165
	v_and_b32_e32 v177, 0xffff0000, v165
	v_pk_add_f32 v[12:13], v[12:13], v[170:171]
	v_pk_add_f32 v[14:15], v[14:15], v[172:173]
	v_pk_add_f32 v[8:9], v[8:9], v[174:175]
	v_pk_add_f32 v[10:11], v[10:11], v[176:177]
	v_cvt_pk_bf16_f32 v162, v12, v13
	v_cvt_pk_bf16_f32 v163, v14, v15
	v_cvt_pk_bf16_f32 v164, v8, v9
	v_cvt_pk_bf16_f32 v165, v10, v11
	v_mul_f32_e32 v178, v12, v12
	v_fmac_f32_e32 v178, v13, v13
	v_fmac_f32_e32 v178, v14, v14
	v_fmac_f32_e32 v178, v15, v15
	v_fmac_f32_e32 v178, v8, v8
	v_fmac_f32_e32 v178, v9, v9
	v_fmac_f32_e32 v178, v10, v10
	v_fmac_f32_e32 v178, v11, v11
	v_lshlrev_b32_e32 v170, 16, v166
	v_and_b32_e32 v171, 0xffff0000, v166
	v_lshlrev_b32_e32 v172, 16, v167
	v_and_b32_e32 v173, 0xffff0000, v167
	v_lshlrev_b32_e32 v174, 16, v168
	v_and_b32_e32 v175, 0xffff0000, v168
	v_lshlrev_b32_e32 v176, 16, v169
	v_and_b32_e32 v177, 0xffff0000, v169
	v_pk_add_f32 v[4:5], v[4:5], v[170:171]
	v_pk_add_f32 v[6:7], v[6:7], v[172:173]
	v_pk_add_f32 v[0:1], v[0:1], v[174:175]
	v_pk_add_f32 v[2:3], v[2:3], v[176:177]
	v_cvt_pk_bf16_f32 v166, v4, v5
	v_cvt_pk_bf16_f32 v167, v6, v7
	v_cvt_pk_bf16_f32 v168, v0, v1
	v_cvt_pk_bf16_f32 v169, v2, v3
	v_fmac_f32_e32 v178, v4, v4
	v_fmac_f32_e32 v178, v5, v5
	v_fmac_f32_e32 v178, v6, v6
	v_fmac_f32_e32 v178, v7, v7
	v_fmac_f32_e32 v178, v0, v0
	v_fmac_f32_e32 v178, v1, v1
	v_fmac_f32_e32 v178, v2, v2
	v_fmac_f32_e32 v178, v3, v3
	v_mov_b32_e32 v146, v162
	v_mov_b32_e32 v147, v163
	v_mov_b32_e32 v148, v164
	v_mov_b32_e32 v149, v165
	v_mov_b32_dpp v162, v166 row_ror:8 row_mask:0xf bank_mask:0xc
	v_mov_b32_dpp v163, v167 row_ror:8 row_mask:0xf bank_mask:0xc
	v_mov_b32_dpp v164, v168 row_ror:8 row_mask:0xf bank_mask:0xc
	v_mov_b32_dpp v165, v169 row_ror:8 row_mask:0xf bank_mask:0xc
	v_mov_b32_dpp v166, v146 row_ror:8 row_mask:0xf bank_mask:0x3
	v_mov_b32_dpp v167, v147 row_ror:8 row_mask:0xf bank_mask:0x3
	v_mov_b32_dpp v168, v148 row_ror:8 row_mask:0xf bank_mask:0x3
	v_mov_b32_dpp v169, v149 row_ror:8 row_mask:0xf bank_mask:0x3
	v_mov_b32_e32 v179, v178
	s_nop 1
	v_permlane16_swap_b32_e32 v178, v179
	v_add_f32_e32 v178, v178, v179
	v_mov_b32_e32 v179, v178
	s_nop 1
	v_permlane32_swap_b32_e32 v178, v179
	v_add_f32_e32 v187, v178, v179
	s_mov_b64 s[62:63], 0x8000
	v_lshl_add_u64 v[144:145], v[190:191], 0, s[62:63]
	global_store_dwordx4 v[190:191], v[204:207], off
	global_store_dwordx4 v[144:145], v[208:211], off
	s_mov_b64 s[60:61], 0x10000
	s_mov_b64 s[62:63], 0x18000
	v_lshl_add_u64 v[142:143], v[190:191], 0, s[60:61]
	v_lshl_add_u64 v[144:145], v[190:191], 0, s[62:63]
	global_store_dwordx4 v[142:143], v[212:215], off
	global_store_dwordx4 v[144:145], v[216:219], off
	s_mov_b64 s[60:61], 0x20000
	s_mov_b64 s[62:63], 0x28000
	v_lshl_add_u64 v[142:143], v[190:191], 0, s[60:61]
	v_lshl_add_u64 v[144:145], v[190:191], 0, s[62:63]
	global_store_dwordx4 v[142:143], v[220:223], off
	global_store_dwordx4 v[144:145], v[224:227], off
	s_mov_b64 s[60:61], 0x30000
	s_mov_b64 s[62:63], 0x38000
	v_lshl_add_u64 v[142:143], v[190:191], 0, s[60:61]
	v_lshl_add_u64 v[144:145], v[190:191], 0, s[62:63]
	global_store_dwordx4 v[142:143], v[228:231], off
	global_store_dwordx4 v[144:145], v[232:235], off
	s_mov_b64 s[60:61], 0x80000
	s_mov_b64 s[62:63], 0x88000
	v_lshl_add_u64 v[142:143], v[190:191], 0, s[60:61]
	v_lshl_add_u64 v[144:145], v[190:191], 0, s[62:63]
	global_store_dwordx4 v[142:143], v[236:239], off
	global_store_dwordx4 v[144:145], v[240:243], off
	s_mov_b64 s[60:61], 0x90000
	s_mov_b64 s[62:63], 0x98000
	v_lshl_add_u64 v[142:143], v[190:191], 0, s[60:61]
	v_lshl_add_u64 v[144:145], v[190:191], 0, s[62:63]
	global_store_dwordx4 v[142:143], v[244:247], off
	global_store_dwordx4 v[144:145], v[248:251], off
	s_mov_b64 s[60:61], 0xa0000
	s_mov_b64 s[62:63], 0xa8000
	v_lshl_add_u64 v[142:143], v[190:191], 0, s[60:61]
	v_lshl_add_u64 v[144:145], v[190:191], 0, s[62:63]
	global_store_dwordx4 v[142:143], v[154:157], off
	global_store_dwordx4 v[144:145], v[158:161], off
	s_mov_b64 s[60:61], 0xb0000
	s_mov_b64 s[62:63], 0xb8000
	v_lshl_add_u64 v[142:143], v[190:191], 0, s[60:61]
	v_lshl_add_u64 v[144:145], v[190:191], 0, s[62:63]
	global_store_dwordx4 v[142:143], v[162:165], off
	global_store_dwordx4 v[144:145], v[166:169], off
	s_and_saveexec_b64 s[16:17], vcc
	global_atomic_add_f32 v[140:141], v180, off
	global_atomic_add_f32 v[140:141], v181, off offset:64
	global_atomic_add_f32 v[140:141], v182, off offset:128
	global_atomic_add_f32 v[140:141], v183, off offset:192
	global_atomic_add_f32 v[140:141], v184, off offset:512
	global_atomic_add_f32 v[140:141], v185, off offset:576
	global_atomic_add_f32 v[140:141], v186, off offset:640
	global_atomic_add_f32 v[140:141], v187, off offset:704
	s_or_b64 exec, exec, s[16:17]
	s_andn2_b64 vcc, exec, s[8:9]
	s_mov_b64 s[8:9], -1
	s_cbranch_vccnz .LBB0_1207
	s_andn2_b64 vcc, exec, s[0:1]
	s_cbranch_vccnz .LBB0_1206
	s_barrier
	s_branch .LBB0_1206
